# sample chain: S5 sample step and residual-updating sample GEMMs request their far rows early; q row requested before the task barrier
# baseline (speedup 1.0000x reference)
.LBB11_791:
	global_load_dword v44, v1, s[46:47]
	s_add_u32 s0, s88, 0x15900000
	s_addc_u32 s1, s89, 0
	s_add_u32 s6, s88, 0x11800000
	s_addc_u32 s7, s89, 0
	global_load_dword v234, v1, s[0:1] offset:16
	global_load_dword v234, v209, s[88:89]
	global_load_dword v234, v1, s[6:7] offset:16
	global_load_dword v234, v210, s[88:89]
	v_lshl_add_u64 v[232:233], v[40:41], 0, s[90:91]
	global_load_dword v234, v[232:233], off
	v_lshl_add_u64 v[232:233], v[38:39], 0, s[90:91]
	global_load_dword v234, v[232:233], off
	v_mov_b32_e32 v91, 0
	s_waitcnt vmcnt(0)
	v_fmamk_f32 v44, v44, 0x3a800000, v206
	v_cmp_gt_f32_e64 s[44:45], s77, v44
	v_mul_f32_e32 v45, 0x4b800000, v44
	s_nop 0
	v_cndmask_b32_e64 v44, v44, v45, s[44:45]
	v_rsq_f32_e32 v44, v44
	s_nop 0
	v_mul_f32_e32 v45, 0x45800000, v44
	v_cndmask_b32_e64 v112, v44, v45, s[44:45]
	s_waitcnt lgkmcnt(0)
	global_load_dwordx4 v[44:47], v1, s[0:1] offset:16
	global_load_dwordx4 v[48:51], v209, s[88:89]
	global_load_dwordx4 v[92:95], v1, s[6:7] offset:16
	global_load_dwordx4 v[52:55], v210, s[88:89]
	global_load_dwordx4 v[96:99], v1, s[56:57] offset:48
	global_load_dwordx4 v[100:103], v1, s[56:57] offset:32
	global_load_dwordx4 v[104:107], v1, s[56:57] offset:16
	global_load_dwordx4 v[108:111], v1, s[56:57]
	s_mov_b32 s0, 0x8100000
	s_waitcnt vmcnt(6)
	v_lshlrev_b32_e32 v56, 16, v48
	v_and_b32_e32 v57, 0xffff0000, v48
	s_waitcnt vmcnt(4)
	v_lshlrev_b32_e32 v58, 16, v52
	v_and_b32_e32 v59, 0xffff0000, v52
	v_lshlrev_b32_e32 v48, 16, v49
	v_and_b32_e32 v49, 0xffff0000, v49
	v_lshlrev_b32_e32 v52, 16, v53
	v_and_b32_e32 v53, 0xffff0000, v53
	v_pk_add_f32 v[56:57], v[56:57], v[58:59]
	v_pk_add_f32 v[48:49], v[48:49], v[52:53]
	v_pk_mul_f32 v[52:53], v[112:113], v[56:57] op_sel_hi:[0,1]
	v_pk_mul_f32 v[48:49], v[112:113], v[48:49] op_sel_hi:[0,1]
	s_waitcnt vmcnt(0)
	v_pk_mul_f32 v[56:57], v[110:111], v[48:49]
	v_pk_mul_f32 v[58:59], v[108:109], v[52:53]
	v_lshlrev_b32_e32 v48, 16, v50
	v_and_b32_e32 v49, 0xffff0000, v50
	v_lshlrev_b32_e32 v52, 16, v54
	v_and_b32_e32 v53, 0xffff0000, v54
	v_pk_add_f32 v[48:49], v[48:49], v[52:53]
	v_lshlrev_b32_e32 v50, 16, v51
	v_and_b32_e32 v51, 0xffff0000, v51
	v_lshlrev_b32_e32 v52, 16, v55
	v_and_b32_e32 v53, 0xffff0000, v55
	v_pk_add_f32 v[50:51], v[50:51], v[52:53]
	v_pk_mul_f32 v[48:49], v[112:113], v[48:49] op_sel_hi:[0,1]
	v_pk_mul_f32 v[50:51], v[112:113], v[50:51] op_sel_hi:[0,1]
	v_pk_mul_f32 v[52:53], v[106:107], v[50:51]
	v_pk_mul_f32 v[54:55], v[104:105], v[48:49]
	v_lshlrev_b32_e32 v48, 16, v44
	v_and_b32_e32 v49, 0xffff0000, v44
	v_lshlrev_b32_e32 v50, 16, v92
	v_and_b32_e32 v51, 0xffff0000, v92
	v_pk_add_f32 v[48:49], v[48:49], v[50:51]
	v_lshlrev_b32_e32 v44, 16, v45
	v_and_b32_e32 v45, 0xffff0000, v45
	v_lshlrev_b32_e32 v50, 16, v93
	v_and_b32_e32 v51, 0xffff0000, v93
	v_pk_add_f32 v[44:45], v[44:45], v[50:51]
	v_pk_mul_f32 v[50:51], v[112:113], v[48:49] op_sel_hi:[0,1]
	v_pk_mul_f32 v[44:45], v[112:113], v[44:45] op_sel_hi:[0,1]
	v_pk_mul_f32 v[48:49], v[102:103], v[44:45]
	v_lshlrev_b32_e32 v44, 16, v46
	v_and_b32_e32 v45, 0xffff0000, v46
	v_lshlrev_b32_e32 v92, 16, v94
	v_and_b32_e32 v93, 0xffff0000, v94
	v_pk_add_f32 v[44:45], v[44:45], v[92:93]
	v_lshlrev_b32_e32 v46, 16, v47
	v_and_b32_e32 v47, 0xffff0000, v47
	v_lshlrev_b32_e32 v92, 16, v95
	v_and_b32_e32 v93, 0xffff0000, v95
	v_pk_add_f32 v[46:47], v[46:47], v[92:93]
	v_pk_mul_f32 v[92:93], v[112:113], v[44:45] op_sel_hi:[0,1]
	v_lshl_add_u64 v[94:95], v[40:41], 0, s[90:91]
	v_pk_mul_f32 v[44:45], v[112:113], v[46:47] op_sel_hi:[0,1]
	v_pk_mul_f32 v[46:47], v[96:97], v[92:93]
	global_load_dword v96, v[94:95], off
	v_lshl_add_u64 v[94:95], v[38:39], 0, s[90:91]
	global_load_dword v94, v[94:95], off
	v_fma_f32 v93, v2, v58, 0
	v_fma_f32 v92, v3, v58, 0
	v_fmac_f32_e32 v93, v4, v59
	v_fmac_f32_e32 v92, v5, v59
	v_fmac_f32_e32 v93, v6, v56
	v_fmac_f32_e32 v92, v7, v56
	v_fmac_f32_e32 v93, v8, v57
	v_fmac_f32_e32 v92, v9, v57
	v_fmac_f32_e32 v93, v10, v54
	v_fmac_f32_e32 v92, v11, v54
	v_fmac_f32_e32 v93, v12, v55
	v_fmac_f32_e32 v92, v13, v55
	v_fmac_f32_e32 v93, v14, v52
	v_fmac_f32_e32 v92, v15, v52
	v_pk_mul_f32 v[50:51], v[100:101], v[50:51]
	v_fmac_f32_e32 v93, v16, v53
	v_fmac_f32_e32 v92, v17, v53
	v_fmac_f32_e32 v93, v18, v50
	v_fmac_f32_e32 v92, v19, v50
	v_fmac_f32_e32 v93, v20, v51
	v_fmac_f32_e32 v92, v21, v51
	v_fmac_f32_e32 v93, v22, v48
	v_fmac_f32_e32 v92, v23, v48
	v_fmac_f32_e32 v93, v24, v49
	v_fmac_f32_e32 v92, v25, v49
	v_fmac_f32_e32 v93, v26, v46
	v_fmac_f32_e32 v92, v27, v46
	v_pk_mul_f32 v[44:45], v[98:99], v[44:45]
	v_fmac_f32_e32 v93, v28, v47
	v_fmac_f32_e32 v92, v29, v47
	v_fmac_f32_e32 v93, v30, v44
	v_fmac_f32_e32 v92, v31, v44
	v_fmac_f32_e32 v93, v32, v45
	v_fmac_f32_e32 v92, v33, v45
	s_waitcnt vmcnt(0)
	v_mul_f32_e32 v95, v35, v94
	v_mul_f32_e32 v94, v34, v94
	v_fma_f32 v95, v34, v96, -v95
	v_fmac_f32_e32 v94, v35, v96
	v_add_f32_e32 v93, v95, v93
	v_add_f32_e32 v92, v94, v92
	v_lshl_add_u64 v[94:95], v[36:37], 0, s[90:91]
	v_add_co_u32_e64 v96, s[44:45], s0, v94
	s_mov_b32 s0, 0x8500000
	s_nop 0
	v_addc_co_u32_e64 v97, s[44:45], 0, v95, s[44:45]
	v_add_co_u32_e64 v94, s[44:45], s0, v94
	global_store_dword v[96:97], v93, off
	s_nop 0
	v_addc_co_u32_e64 v95, s[44:45], 0, v95, s[44:45]
	global_store_dword v[94:95], v92, off
	s_load_dwordx2 s[0:1], s[58:59], 0xc8
	s_lshl_b64 s[6:7], s[60:61], 2
	v_mbcnt_lo_u32_b32 v231, -1, 0
	v_mbcnt_hi_u32_b32 v231, -1, v231
	v_lshlrev_b32_e32 v231, 2, v231
	s_waitcnt lgkmcnt(0)
	s_add_u32 s0, s0, s6
	s_addc_u32 s1, s1, s7
	s_and_saveexec_b64 s[44:45], vcc
	global_load_dword v230, v231, s[0:1]
	s_or_b64 exec, exec, s[44:45]
	v_mul_f32_e32 v214, v67, v92
	v_fma_f32 v214, v0, v93, -v214
	v_mul_f32_e32 v215, v68, v92
	v_fma_f32 v215, v60, v93, -v215
	v_mul_f32_e32 v216, v69, v92
	v_fma_f32 v216, v61, v93, -v216
	v_mul_f32_e32 v217, v70, v92
	v_fma_f32 v217, v62, v93, -v217
	v_mul_f32_e32 v218, v71, v92
	v_fma_f32 v218, v63, v93, -v218
	v_mul_f32_e32 v219, v72, v92
	v_fma_f32 v219, v64, v93, -v219
	v_mul_f32_e32 v220, v73, v92
	v_fma_f32 v220, v65, v93, -v220
	v_mul_f32_e32 v221, v74, v92
	v_fma_f32 v221, v66, v93, -v221
	v_mul_f32_e32 v222, v83, v92
	v_fma_f32 v222, v75, v93, -v222
	v_mul_f32_e32 v223, v84, v92
	v_fma_f32 v223, v76, v93, -v223
	v_mul_f32_e32 v224, v85, v92
	v_fma_f32 v224, v77, v93, -v224
	v_mul_f32_e32 v225, v86, v92
	v_fma_f32 v225, v78, v93, -v225
	v_mul_f32_e32 v226, v87, v92
	v_fma_f32 v226, v79, v93, -v226
	v_mul_f32_e32 v227, v88, v92
	v_fma_f32 v227, v80, v93, -v227
	v_mul_f32_e32 v228, v89, v92
	v_fma_f32 v228, v81, v93, -v228
	v_mul_f32_e32 v229, v90, v92
	v_fma_f32 v229, v82, v93, -v229
	ds_bpermute_b32 v116, v200, v214
	ds_bpermute_b32 v117, v200, v215
	ds_bpermute_b32 v118, v200, v216
	ds_bpermute_b32 v119, v200, v217
	ds_bpermute_b32 v120, v200, v218
	ds_bpermute_b32 v121, v200, v219
	ds_bpermute_b32 v122, v200, v220
	ds_bpermute_b32 v123, v200, v221
	s_waitcnt lgkmcnt(7)
	v_add_f32_e32 v214, v214, v116
	s_waitcnt lgkmcnt(6)
	v_add_f32_e32 v215, v215, v117
	s_waitcnt lgkmcnt(5)
	v_add_f32_e32 v216, v216, v118
	s_waitcnt lgkmcnt(4)
	v_add_f32_e32 v217, v217, v119
	s_waitcnt lgkmcnt(3)
	v_add_f32_e32 v218, v218, v120
	s_waitcnt lgkmcnt(2)
	v_add_f32_e32 v219, v219, v121
	s_waitcnt lgkmcnt(1)
	v_add_f32_e32 v220, v220, v122
	s_waitcnt lgkmcnt(0)
	v_add_f32_e32 v221, v221, v123
	ds_bpermute_b32 v116, v201, v214
	ds_bpermute_b32 v117, v201, v215
	ds_bpermute_b32 v118, v201, v216
	ds_bpermute_b32 v119, v201, v217
	ds_bpermute_b32 v120, v201, v218
	ds_bpermute_b32 v121, v201, v219
	ds_bpermute_b32 v122, v201, v220
	ds_bpermute_b32 v123, v201, v221
	s_waitcnt lgkmcnt(7)
	v_add_f32_e32 v214, v214, v116
	s_waitcnt lgkmcnt(6)
	v_add_f32_e32 v215, v215, v117
	s_waitcnt lgkmcnt(5)
	v_add_f32_e32 v216, v216, v118
	s_waitcnt lgkmcnt(4)
	v_add_f32_e32 v217, v217, v119
	s_waitcnt lgkmcnt(3)
	v_add_f32_e32 v218, v218, v120
	s_waitcnt lgkmcnt(2)
	v_add_f32_e32 v219, v219, v121
	s_waitcnt lgkmcnt(1)
	v_add_f32_e32 v220, v220, v122
	s_waitcnt lgkmcnt(0)
	v_add_f32_e32 v221, v221, v123
	ds_bpermute_b32 v116, v202, v214
	ds_bpermute_b32 v117, v202, v215
	ds_bpermute_b32 v118, v202, v216
	ds_bpermute_b32 v119, v202, v217
	ds_bpermute_b32 v120, v202, v218
	ds_bpermute_b32 v121, v202, v219
	ds_bpermute_b32 v122, v202, v220
	ds_bpermute_b32 v123, v202, v221
	s_waitcnt lgkmcnt(7)
	v_add_f32_e32 v214, v214, v116
	s_waitcnt lgkmcnt(6)
	v_add_f32_e32 v215, v215, v117
	s_waitcnt lgkmcnt(5)
	v_add_f32_e32 v216, v216, v118
	s_waitcnt lgkmcnt(4)
	v_add_f32_e32 v217, v217, v119
	s_waitcnt lgkmcnt(3)
	v_add_f32_e32 v218, v218, v120
	s_waitcnt lgkmcnt(2)
	v_add_f32_e32 v219, v219, v121
	s_waitcnt lgkmcnt(1)
	v_add_f32_e32 v220, v220, v122
	s_waitcnt lgkmcnt(0)
	v_add_f32_e32 v221, v221, v123
	ds_bpermute_b32 v116, v203, v214
	ds_bpermute_b32 v117, v203, v215
	ds_bpermute_b32 v118, v203, v216
	ds_bpermute_b32 v119, v203, v217
	ds_bpermute_b32 v120, v203, v218
	ds_bpermute_b32 v121, v203, v219
	ds_bpermute_b32 v122, v203, v220
	ds_bpermute_b32 v123, v203, v221
	s_waitcnt lgkmcnt(7)
	v_add_f32_e32 v214, v214, v116
	s_waitcnt lgkmcnt(6)
	v_add_f32_e32 v215, v215, v117
	s_waitcnt lgkmcnt(5)
	v_add_f32_e32 v216, v216, v118
	s_waitcnt lgkmcnt(4)
	v_add_f32_e32 v217, v217, v119
	s_waitcnt lgkmcnt(3)
	v_add_f32_e32 v218, v218, v120
	s_waitcnt lgkmcnt(2)
	v_add_f32_e32 v219, v219, v121
	s_waitcnt lgkmcnt(1)
	v_add_f32_e32 v220, v220, v122
	s_waitcnt lgkmcnt(0)
	v_add_f32_e32 v221, v221, v123
	ds_bpermute_b32 v116, v204, v214
	ds_bpermute_b32 v117, v204, v215
	ds_bpermute_b32 v118, v204, v216
	ds_bpermute_b32 v119, v204, v217
	ds_bpermute_b32 v120, v204, v218
	ds_bpermute_b32 v121, v204, v219
	ds_bpermute_b32 v122, v204, v220
	ds_bpermute_b32 v123, v204, v221
	s_waitcnt lgkmcnt(7)
	v_add_f32_e32 v214, v214, v116
	s_waitcnt lgkmcnt(6)
	v_add_f32_e32 v215, v215, v117
	s_waitcnt lgkmcnt(5)
	v_add_f32_e32 v216, v216, v118
	s_waitcnt lgkmcnt(4)
	v_add_f32_e32 v217, v217, v119
	s_waitcnt lgkmcnt(3)
	v_add_f32_e32 v218, v218, v120
	s_waitcnt lgkmcnt(2)
	v_add_f32_e32 v219, v219, v121
	s_waitcnt lgkmcnt(1)
	v_add_f32_e32 v220, v220, v122
	s_waitcnt lgkmcnt(0)
	v_add_f32_e32 v221, v221, v123
	ds_bpermute_b32 v116, v205, v214
	ds_bpermute_b32 v117, v205, v215
	ds_bpermute_b32 v118, v205, v216
	ds_bpermute_b32 v119, v205, v217
	ds_bpermute_b32 v120, v205, v218
	ds_bpermute_b32 v121, v205, v219
	ds_bpermute_b32 v122, v205, v220
	ds_bpermute_b32 v123, v205, v221
	s_waitcnt lgkmcnt(7)
	v_add_f32_e32 v214, v214, v116
	s_waitcnt lgkmcnt(6)
	v_add_f32_e32 v215, v215, v117
	s_waitcnt lgkmcnt(5)
	v_add_f32_e32 v216, v216, v118
	s_waitcnt lgkmcnt(4)
	v_add_f32_e32 v217, v217, v119
	s_waitcnt lgkmcnt(3)
	v_add_f32_e32 v218, v218, v120
	s_waitcnt lgkmcnt(2)
	v_add_f32_e32 v219, v219, v121
	s_waitcnt lgkmcnt(1)
	v_add_f32_e32 v220, v220, v122
	s_waitcnt lgkmcnt(0)
	v_add_f32_e32 v221, v221, v123
	ds_bpermute_b32 v124, v200, v222
	ds_bpermute_b32 v125, v200, v223
	ds_bpermute_b32 v126, v200, v224
	ds_bpermute_b32 v127, v200, v225
	ds_bpermute_b32 v128, v200, v226
	ds_bpermute_b32 v129, v200, v227
	ds_bpermute_b32 v130, v200, v228
	ds_bpermute_b32 v131, v200, v229
	s_waitcnt lgkmcnt(7)
	v_add_f32_e32 v222, v222, v124
	s_waitcnt lgkmcnt(6)
	v_add_f32_e32 v223, v223, v125
	s_waitcnt lgkmcnt(5)
	v_add_f32_e32 v224, v224, v126
	s_waitcnt lgkmcnt(4)
	v_add_f32_e32 v225, v225, v127
	s_waitcnt lgkmcnt(3)
	v_add_f32_e32 v226, v226, v128
	s_waitcnt lgkmcnt(2)
	v_add_f32_e32 v227, v227, v129
	s_waitcnt lgkmcnt(1)
	v_add_f32_e32 v228, v228, v130
	s_waitcnt lgkmcnt(0)
	v_add_f32_e32 v229, v229, v131
	ds_bpermute_b32 v124, v201, v222
	ds_bpermute_b32 v125, v201, v223
	ds_bpermute_b32 v126, v201, v224
	ds_bpermute_b32 v127, v201, v225
	ds_bpermute_b32 v128, v201, v226
	ds_bpermute_b32 v129, v201, v227
	ds_bpermute_b32 v130, v201, v228
	ds_bpermute_b32 v131, v201, v229
	s_waitcnt lgkmcnt(7)
	v_add_f32_e32 v222, v222, v124
	s_waitcnt lgkmcnt(6)
	v_add_f32_e32 v223, v223, v125
	s_waitcnt lgkmcnt(5)
	v_add_f32_e32 v224, v224, v126
	s_waitcnt lgkmcnt(4)
	v_add_f32_e32 v225, v225, v127
	s_waitcnt lgkmcnt(3)
	v_add_f32_e32 v226, v226, v128
	s_waitcnt lgkmcnt(2)
	v_add_f32_e32 v227, v227, v129
	s_waitcnt lgkmcnt(1)
	v_add_f32_e32 v228, v228, v130
	s_waitcnt lgkmcnt(0)
	v_add_f32_e32 v229, v229, v131
	ds_bpermute_b32 v124, v202, v222
	ds_bpermute_b32 v125, v202, v223
	ds_bpermute_b32 v126, v202, v224
	ds_bpermute_b32 v127, v202, v225
	ds_bpermute_b32 v128, v202, v226
	ds_bpermute_b32 v129, v202, v227
	ds_bpermute_b32 v130, v202, v228
	ds_bpermute_b32 v131, v202, v229
	s_waitcnt lgkmcnt(7)
	v_add_f32_e32 v222, v222, v124
	s_waitcnt lgkmcnt(6)
	v_add_f32_e32 v223, v223, v125
	s_waitcnt lgkmcnt(5)
	v_add_f32_e32 v224, v224, v126
	s_waitcnt lgkmcnt(4)
	v_add_f32_e32 v225, v225, v127
	s_waitcnt lgkmcnt(3)
	v_add_f32_e32 v226, v226, v128
	s_waitcnt lgkmcnt(2)
	v_add_f32_e32 v227, v227, v129
	s_waitcnt lgkmcnt(1)
	v_add_f32_e32 v228, v228, v130
	s_waitcnt lgkmcnt(0)
	v_add_f32_e32 v229, v229, v131
	ds_bpermute_b32 v124, v203, v222
	ds_bpermute_b32 v125, v203, v223
	ds_bpermute_b32 v126, v203, v224
	ds_bpermute_b32 v127, v203, v225
	ds_bpermute_b32 v128, v203, v226
	ds_bpermute_b32 v129, v203, v227
	ds_bpermute_b32 v130, v203, v228
	ds_bpermute_b32 v131, v203, v229
	s_waitcnt lgkmcnt(7)
	v_add_f32_e32 v222, v222, v124
	s_waitcnt lgkmcnt(6)
	v_add_f32_e32 v223, v223, v125
	s_waitcnt lgkmcnt(5)
	v_add_f32_e32 v224, v224, v126
	s_waitcnt lgkmcnt(4)
	v_add_f32_e32 v225, v225, v127
	s_waitcnt lgkmcnt(3)
	v_add_f32_e32 v226, v226, v128
	s_waitcnt lgkmcnt(2)
	v_add_f32_e32 v227, v227, v129
	s_waitcnt lgkmcnt(1)
	v_add_f32_e32 v228, v228, v130
	s_waitcnt lgkmcnt(0)
	v_add_f32_e32 v229, v229, v131
	ds_bpermute_b32 v124, v204, v222
	ds_bpermute_b32 v125, v204, v223
	ds_bpermute_b32 v126, v204, v224
	ds_bpermute_b32 v127, v204, v225
	ds_bpermute_b32 v128, v204, v226
	ds_bpermute_b32 v129, v204, v227
	ds_bpermute_b32 v130, v204, v228
	ds_bpermute_b32 v131, v204, v229
	s_waitcnt lgkmcnt(7)
	v_add_f32_e32 v222, v222, v124
	s_waitcnt lgkmcnt(6)
	v_add_f32_e32 v223, v223, v125
	s_waitcnt lgkmcnt(5)
	v_add_f32_e32 v224, v224, v126
	s_waitcnt lgkmcnt(4)
	v_add_f32_e32 v225, v225, v127
	s_waitcnt lgkmcnt(3)
	v_add_f32_e32 v226, v226, v128
	s_waitcnt lgkmcnt(2)
	v_add_f32_e32 v227, v227, v129
	s_waitcnt lgkmcnt(1)
	v_add_f32_e32 v228, v228, v130
	s_waitcnt lgkmcnt(0)
	v_add_f32_e32 v229, v229, v131
	ds_bpermute_b32 v124, v205, v222
	ds_bpermute_b32 v125, v205, v223
	ds_bpermute_b32 v126, v205, v224
	ds_bpermute_b32 v127, v205, v225
	ds_bpermute_b32 v128, v205, v226
	ds_bpermute_b32 v129, v205, v227
	ds_bpermute_b32 v130, v205, v228
	ds_bpermute_b32 v131, v205, v229
	s_waitcnt lgkmcnt(7)
	v_add_f32_e32 v222, v222, v124
	s_waitcnt lgkmcnt(6)
	v_add_f32_e32 v223, v223, v125
	s_waitcnt lgkmcnt(5)
	v_add_f32_e32 v224, v224, v126
	s_waitcnt lgkmcnt(4)
	v_add_f32_e32 v225, v225, v127
	s_waitcnt lgkmcnt(3)
	v_add_f32_e32 v226, v226, v128
	s_waitcnt lgkmcnt(2)
	v_add_f32_e32 v227, v227, v129
	s_waitcnt lgkmcnt(1)
	v_add_f32_e32 v228, v228, v130
	s_waitcnt lgkmcnt(0)
	v_add_f32_e32 v229, v229, v131
	s_waitcnt vmcnt(0)
	s_and_saveexec_b64 s[44:45], s[10:11]
	v_fma_f32 v91, v58, v230, v214
	s_or_b64 exec, exec, s[44:45]
	s_and_saveexec_b64 s[44:45], s[12:13]
	v_fma_f32 v91, v59, v230, v215
	s_or_b64 exec, exec, s[44:45]
	s_and_saveexec_b64 s[44:45], s[14:15]
	v_fma_f32 v91, v56, v230, v216
	s_or_b64 exec, exec, s[44:45]
	s_and_saveexec_b64 s[44:45], s[16:17]
	v_fma_f32 v91, v57, v230, v217
	s_or_b64 exec, exec, s[44:45]
	s_and_saveexec_b64 s[44:45], s[18:19]
	v_fma_f32 v91, v54, v230, v218
	s_or_b64 exec, exec, s[44:45]
	s_and_saveexec_b64 s[44:45], s[20:21]
	v_fma_f32 v91, v55, v230, v219
	s_or_b64 exec, exec, s[44:45]
	s_and_saveexec_b64 s[44:45], s[22:23]
	v_fma_f32 v91, v52, v230, v220
	s_or_b64 exec, exec, s[44:45]
	s_and_saveexec_b64 s[44:45], s[24:25]
	v_fma_f32 v91, v53, v230, v221
	s_or_b64 exec, exec, s[44:45]
	s_and_saveexec_b64 s[44:45], s[26:27]
	v_fma_f32 v91, v50, v230, v222
	s_or_b64 exec, exec, s[44:45]
	s_and_saveexec_b64 s[44:45], s[28:29]
	v_fma_f32 v91, v51, v230, v223
	s_or_b64 exec, exec, s[44:45]
	s_and_saveexec_b64 s[44:45], s[30:31]
	v_fma_f32 v91, v48, v230, v224
	s_or_b64 exec, exec, s[44:45]
	s_and_saveexec_b64 s[44:45], s[34:35]
	v_fma_f32 v91, v49, v230, v225
	s_or_b64 exec, exec, s[44:45]
	s_and_saveexec_b64 s[44:45], s[36:37]
	v_fma_f32 v91, v46, v230, v226
	s_or_b64 exec, exec, s[44:45]
	s_and_saveexec_b64 s[44:45], s[38:39]
	v_fma_f32 v91, v47, v230, v227
	s_or_b64 exec, exec, s[44:45]
	s_and_saveexec_b64 s[44:45], s[40:41]
	v_fma_f32 v91, v44, v230, v228
	s_or_b64 exec, exec, s[44:45]
	s_and_saveexec_b64 s[44:45], s[42:43]
	v_fma_f32 v91, v45, v230, v229
	s_or_b64 exec, exec, s[44:45]
	s_and_saveexec_b64 s[44:45], vcc
	s_cbranch_execz .LBB11_790
	v_mul_f32_e32 v44, 0x3d922279, v91
	v_fmaak_f32 v44, v91, v44, 0x3fcc422a
	v_mul_f32_e32 v44, v91, v44
	v_mul_f32_e32 v44, 0xbfb8aa3b, v44
	v_exp_f32_e32 v44, v44
	s_nop 0
	v_add_f32_e32 v44, 1.0, v44
	v_rcp_f32_e32 v44, v44
	s_nop 0
	v_mul_f32_e32 v44, v91, v44
	s_waitcnt lgkmcnt(0)
	v_cvt_pk_bf16_f32 v46, v44, v1
	v_lshl_add_u64 v[44:45], s[88:89], 0, v[42:43]
	global_store_short v[44:45], v46, off
	s_branch .LBB11_790

.LBB11_1027:
	s_ashr_i32 s0, s6, 31
	s_lshr_b32 s0, s0, 30
	s_add_i32 s0, s6, s0
	s_ashr_i32 s9, s0, 2
	s_lshl_b32 s0, s9, 7
	v_subrev_u32_e32 v84, s0, v96
	v_ashrrev_i32_e32 v85, 31, v84
	s_waitcnt lgkmcnt(0)
	v_lshlrev_b64 v[34:35], 11, v[84:85]
	v_lshl_add_u64 v[34:35], v[66:67], 0, v[34:35]
	global_load_dwordx4 v[62:65], v[34:35], off
	global_load_dwordx4 v[58:61], v[34:35], off offset:64
	global_load_dwordx4 v[54:57], v[34:35], off offset:128
	global_load_dwordx4 v[50:53], v[34:35], off offset:192
	global_load_dwordx4 v[46:49], v[34:35], off offset:256
	global_load_dwordx4 v[42:45], v[34:35], off offset:320
	global_load_dwordx4 v[38:41], v[34:35], off offset:384
	s_nop 0
	global_load_dwordx4 v[34:37], v[34:35], off offset:448
	s_lshl_b32 s0, s9, 5
	s_lshl_b32 s34, s9, 4
	s_lshl_b32 s100, s9, 17
	v_subrev_u32_e32 v252, s100, v97
	v_add_u32_e32 v253, s34, v87
	v_add_lshl_u32 v252, v252, v253, 1
	global_load_dword v254, v252, s[66:67]
	global_load_dword v254, v252, s[64:65]
	s_and_b32 s0, s0, 0xffffff00
	s_and_b32 s1, s34, 0x70
	s_or_b32 s0, s0, s1
	s_barrier
	s_and_saveexec_b64 s[30:31], s[12:13]
	s_cbranch_execz .LBB11_1043
	v_add_u32_e32 v30, s0, v88
	v_ashrrev_i32_e32 v31, 31, v30
	v_lshlrev_b64 v[30:31], 11, v[30:31]
	v_lshl_add_u64 v[30:31], v[68:69], 0, v[30:31]
	global_load_dwordx4 v[30:33], v[30:31], off
	s_or_b64 exec, exec, s[30:31]
	s_and_saveexec_b64 s[30:31], s[14:15]
	s_cbranch_execnz .LBB11_1044

.LBB11_1730:
	s_ashr_i32 s0, s6, 31
	s_lshr_b32 s0, s0, 30
	s_add_i32 s0, s6, s0
	s_ashr_i32 s9, s0, 2
	s_lshl_b32 s0, s9, 7
	v_subrev_u32_e32 v116, s0, v128
	v_ashrrev_i32_e32 v117, 31, v116
	s_waitcnt lgkmcnt(0)
	v_lshlrev_b64 v[34:35], 12, v[116:117]
	v_lshl_add_u64 v[34:35], v[98:99], 0, v[34:35]
	global_load_dwordx4 v[94:97], v[34:35], off
	global_load_dwordx4 v[90:93], v[34:35], off offset:64
	global_load_dwordx4 v[86:89], v[34:35], off offset:128
	global_load_dwordx4 v[82:85], v[34:35], off offset:192
	global_load_dwordx4 v[78:81], v[34:35], off offset:256
	global_load_dwordx4 v[74:77], v[34:35], off offset:320
	global_load_dwordx4 v[70:73], v[34:35], off offset:384
	global_load_dwordx4 v[66:69], v[34:35], off offset:448
	global_load_dwordx4 v[62:65], v[34:35], off offset:512
	global_load_dwordx4 v[58:61], v[34:35], off offset:576
	global_load_dwordx4 v[54:57], v[34:35], off offset:640
	global_load_dwordx4 v[50:53], v[34:35], off offset:704
	global_load_dwordx4 v[46:49], v[34:35], off offset:768
	global_load_dwordx4 v[42:45], v[34:35], off offset:832
	global_load_dwordx4 v[38:41], v[34:35], off offset:896
	s_nop 0
	global_load_dwordx4 v[34:37], v[34:35], off offset:960
	s_lshl_b32 s34, s9, 4
	s_lshl_b32 s100, s9, 17
	v_subrev_u32_e32 v252, s100, v129
	v_add_u32_e32 v253, s34, v119
	v_add_lshl_u32 v252, v252, v253, 1
	global_load_dword v254, v252, s[66:67]
	global_load_dword v254, v252, s[64:65]
	s_barrier
	s_and_saveexec_b64 s[30:31], s[12:13]
	s_cbranch_execz .LBB11_1746
	v_add_u32_e32 v30, s34, v120
	v_ashrrev_i32_e32 v31, 31, v30
	v_lshlrev_b64 v[30:31], 12, v[30:31]
	v_lshl_add_u64 v[30:31], v[100:101], 0, v[30:31]
	global_load_dwordx4 v[30:33], v[30:31], off
	s_or_b64 exec, exec, s[30:31]
	s_and_saveexec_b64 s[30:31], s[14:15]
	s_cbranch_execnz .LBB11_1747

.LBB11_2191:
	s_ashr_i32 s0, s71, 2
	s_add_i32 s10, s0, 0x4000
	s_ashr_i32 s11, s10, 31
	s_lshl_b64 s[88:89], s[10:11], 10
	s_lshl_b64 s[10:11], s[10:11], 11
	s_add_u32 s1, s6, s10
	s_addc_u32 s11, s7, s11
	s_lshl_b32 s10, s71, 8
	s_and_b32 s68, s10, 0x300
	s_lshl_b32 s10, s68, 1
	s_add_u32 s10, s1, s10
	s_addc_u32 s11, s11, 0
	v_lshl_add_u64 v[2:3], v[100:101], 1, s[10:11]
	global_load_dwordx2 v[2:3], v[2:3], off
	s_barrier
	s_ashr_i32 s1, s0, 31
	s_lshl_b64 s[0:1], s[0:1], 18
	s_add_u32 s0, s0, s70
	s_addc_u32 s1, s1, 0
	s_lshl_b64 s[90:91], s[0:1], 2
	s_add_u32 s0, s56, s90
	s_addc_u32 s1, s57, s91
	s_lshl_b32 s10, s68, 2
	s_add_u32 s0, s0, s10
	s_addc_u32 s1, s1, 0
	v_lshl_add_u64 v[62:63], v[100:101], 2, s[0:1]
	s_mov_b32 s0, 0
	s_mov_b64 s[10:11], -1
	s_waitcnt vmcnt(0)
	v_lshlrev_b32_e32 v64, 16, v2
	v_and_b32_e32 v65, 0xffff0000, v2
	v_lshlrev_b32_e32 v66, 16, v3
	v_and_b32_e32 v67, 0xffff0000, v3
	s_branch .LBB11_2193

.LBB11_2430:
	s_ashr_i32 s0, s6, 31
	s_lshr_b32 s0, s0, 30
	s_add_i32 s0, s6, s0
	s_ashr_i32 s9, s0, 2
	s_lshl_b32 s0, s9, 7
	v_subrev_u32_e32 v84, s0, v96
	v_ashrrev_i32_e32 v85, 31, v84
	s_waitcnt lgkmcnt(0)
	v_lshlrev_b64 v[34:35], 11, v[84:85]
	v_lshl_add_u64 v[34:35], v[66:67], 0, v[34:35]
	global_load_dwordx4 v[62:65], v[34:35], off
	global_load_dwordx4 v[58:61], v[34:35], off offset:64
	global_load_dwordx4 v[54:57], v[34:35], off offset:128
	global_load_dwordx4 v[50:53], v[34:35], off offset:192
	global_load_dwordx4 v[46:49], v[34:35], off offset:256
	global_load_dwordx4 v[42:45], v[34:35], off offset:320
	global_load_dwordx4 v[38:41], v[34:35], off offset:384
	s_nop 0
	global_load_dwordx4 v[34:37], v[34:35], off offset:448
	s_lshl_b32 s34, s9, 5
	s_lshl_b32 s100, s9, 17
	v_subrev_u32_e32 v252, s100, v97
	v_add_u32_e32 v253, s34, v87
	v_add_lshl_u32 v252, v252, v253, 1
	global_load_dword v254, v252, s[66:67]
	global_load_dword v254, v252, s[64:65]
	s_barrier
	s_and_saveexec_b64 s[30:31], s[12:13]
	s_cbranch_execz .LBB11_2446
	v_add_u32_e32 v30, s34, v88
	v_ashrrev_i32_e32 v31, 31, v30
	v_lshlrev_b64 v[30:31], 11, v[30:31]
	v_lshl_add_u64 v[30:31], v[68:69], 0, v[30:31]
	global_load_dwordx4 v[30:33], v[30:31], off
	s_or_b64 exec, exec, s[30:31]
	s_and_saveexec_b64 s[30:31], s[14:15]
	s_cbranch_execnz .LBB11_2447

.LBB11_2871:
	s_ashr_i32 s0, s6, 31
	s_lshr_b32 s0, s0, 30
	s_add_i32 s0, s6, s0
	s_ashr_i32 s9, s0, 2
	s_mul_i32 s0, s9, 0xfffa8000
	v_add_u32_e32 v46, s0, v171
	s_waitcnt lgkmcnt(0)
	v_ashrrev_i32_e32 v47, 31, v46
	v_lshl_add_u64 v[46:47], v[46:47], 1, v[134:135]
	global_load_dwordx4 v[130:133], v[46:47], off
	global_load_dwordx4 v[126:129], v[46:47], off offset:64
	global_load_dwordx4 v[122:125], v[46:47], off offset:128
	global_load_dwordx4 v[118:121], v[46:47], off offset:192
	global_load_dwordx4 v[114:117], v[46:47], off offset:256
	global_load_dwordx4 v[110:113], v[46:47], off offset:320
	global_load_dwordx4 v[106:109], v[46:47], off offset:384
	global_load_dwordx4 v[102:105], v[46:47], off offset:448
	global_load_dwordx4 v[98:101], v[46:47], off offset:512
	global_load_dwordx4 v[94:97], v[46:47], off offset:576
	global_load_dwordx4 v[90:93], v[46:47], off offset:640
	global_load_dwordx4 v[86:89], v[46:47], off offset:704
	global_load_dwordx4 v[82:85], v[46:47], off offset:768
	global_load_dwordx4 v[78:81], v[46:47], off offset:832
	global_load_dwordx4 v[74:77], v[46:47], off offset:896
	global_load_dwordx4 v[70:73], v[46:47], off offset:960
	global_load_dwordx4 v[66:69], v[46:47], off offset:1024
	global_load_dwordx4 v[62:65], v[46:47], off offset:1088
	global_load_dwordx4 v[58:61], v[46:47], off offset:1152
	global_load_dwordx4 v[54:57], v[46:47], off offset:1216
	global_load_dwordx4 v[50:53], v[46:47], off offset:1280
	s_nop 0
	global_load_dwordx4 v[46:49], v[46:47], off offset:1344
	s_lshl_b32 s40, s9, 4
	s_lshl_b32 s100, s9, 17
	v_subrev_u32_e32 v252, s100, v173
	v_add_u32_e32 v253, s40, v159
	v_add_lshl_u32 v252, v252, v253, 1
	global_load_dword v254, v252, s[66:67]
	global_load_dword v254, v252, s[64:65]
	s_barrier
	s_and_saveexec_b64 s[38:39], s[12:13]
	s_cbranch_execz .LBB11_2893
	v_add_u32_e32 v0, s40, v160
	v_mad_i64_i32 v[42:43], s[0:1], v0, s73, v[136:137]
	global_load_dwordx4 v[42:45], v[42:43], off
	s_or_b64 exec, exec, s[38:39]
	s_and_saveexec_b64 s[38:39], s[14:15]
	s_cbranch_execnz .LBB11_2894
